# M1 S5 end-state scan loop: same packed 3-op recurrence step
# baseline (speedup 1.0000x reference)
.LBB0_333:
	ds_read2_b32 v[52:53], v51 offset1:68
	ds_read2_b32 v[54:55], v51 offset0:136 offset1:204
	v_add_u32_e32 v58, 0x400, v51
	ds_read2_b32 v[56:57], v58 offset0:16 offset1:84
	ds_read2_b32 v[58:59], v58 offset0:152 offset1:220
	s_add_i32 s2, s2, 8
	s_waitcnt lgkmcnt(3)
	v_lshlrev_b32_e32 v62, 16, v52
	v_pk_mul_f32 v[60:61], v[42:43], v[44:45] op_sel:[0,1] op_sel_hi:[0,0]
	v_and_b32_e32 v63, 0xffff0000, v52
	v_pk_fma_f32 v[60:61], v[40:41], v[44:45], v[60:61] op_sel_hi:[0,1,1] neg_lo:[0,0,1]
	v_pk_add_f32 v[44:45], v[60:61], v[62:63]
	v_lshlrev_b32_e32 v62, 16, v53
	v_pk_mul_f32 v[60:61], v[42:43], v[44:45] op_sel:[0,1] op_sel_hi:[0,0]
	v_and_b32_e32 v63, 0xffff0000, v53
	v_pk_fma_f32 v[60:61], v[40:41], v[44:45], v[60:61] op_sel_hi:[0,1,1] neg_lo:[0,0,1]
	v_pk_add_f32 v[44:45], v[60:61], v[62:63]
	s_waitcnt lgkmcnt(2)
	v_lshlrev_b32_e32 v62, 16, v54
	v_pk_mul_f32 v[60:61], v[42:43], v[44:45] op_sel:[0,1] op_sel_hi:[0,0]
	v_and_b32_e32 v63, 0xffff0000, v54
	v_pk_fma_f32 v[60:61], v[40:41], v[44:45], v[60:61] op_sel_hi:[0,1,1] neg_lo:[0,0,1]
	v_pk_add_f32 v[44:45], v[60:61], v[62:63]
	v_lshlrev_b32_e32 v62, 16, v55
	v_pk_mul_f32 v[60:61], v[42:43], v[44:45] op_sel:[0,1] op_sel_hi:[0,0]
	v_and_b32_e32 v63, 0xffff0000, v55
	v_pk_fma_f32 v[60:61], v[40:41], v[44:45], v[60:61] op_sel_hi:[0,1,1] neg_lo:[0,0,1]
	v_pk_add_f32 v[44:45], v[60:61], v[62:63]
	s_waitcnt lgkmcnt(1)
	v_lshlrev_b32_e32 v62, 16, v56
	v_pk_mul_f32 v[60:61], v[42:43], v[44:45] op_sel:[0,1] op_sel_hi:[0,0]
	v_and_b32_e32 v63, 0xffff0000, v56
	v_pk_fma_f32 v[60:61], v[40:41], v[44:45], v[60:61] op_sel_hi:[0,1,1] neg_lo:[0,0,1]
	v_pk_add_f32 v[44:45], v[60:61], v[62:63]
	v_lshlrev_b32_e32 v62, 16, v57
	v_pk_mul_f32 v[60:61], v[42:43], v[44:45] op_sel:[0,1] op_sel_hi:[0,0]
	v_and_b32_e32 v63, 0xffff0000, v57
	v_pk_fma_f32 v[60:61], v[40:41], v[44:45], v[60:61] op_sel_hi:[0,1,1] neg_lo:[0,0,1]
	v_pk_add_f32 v[44:45], v[60:61], v[62:63]
	s_waitcnt lgkmcnt(0)
	v_lshlrev_b32_e32 v62, 16, v58
	v_pk_mul_f32 v[60:61], v[42:43], v[44:45] op_sel:[0,1] op_sel_hi:[0,0]
	v_and_b32_e32 v63, 0xffff0000, v58
	v_pk_fma_f32 v[60:61], v[40:41], v[44:45], v[60:61] op_sel_hi:[0,1,1] neg_lo:[0,0,1]
	v_pk_add_f32 v[44:45], v[60:61], v[62:63]
	v_lshlrev_b32_e32 v62, 16, v59
	v_pk_mul_f32 v[60:61], v[42:43], v[44:45] op_sel:[0,1] op_sel_hi:[0,0]
	v_and_b32_e32 v63, 0xffff0000, v59
	v_pk_fma_f32 v[60:61], v[40:41], v[44:45], v[60:61] op_sel_hi:[0,1,1] neg_lo:[0,0,1]
	v_pk_add_f32 v[44:45], v[60:61], v[62:63]
	v_add_u32_e32 v51, 0x880, v51
	s_cmp_lt_u32 s2, 24
	s_cbranch_scc1 .LBB0_333
	s_mov_b32 s19, 32
	s_mov_b64 s[2:3], 0
	s_and_b64 vcc, exec, s[16:17]
	s_cbranch_vccz .LBB0_332
	s_add_i32 s2, s18, s7
	s_ashr_i32 s3, s2, 31
	s_lshl_b64 s[2:3], s[2:3], 9
	v_lshl_add_u64 v[4:5], v[38:39], 0, s[2:3]
	s_mov_b32 s14, 1
	s_mov_b64 s[2:3], 0
	s_and_b64 vcc, exec, s[12:13]
	global_store_dwordx2 v[4:5], v[44:45], off
	s_cbranch_vccz .LBB0_331
	s_add_i32 s6, s6, s81
	s_cmpk_gt_i32 s6, 0xff
	s_cbranch_scc0 .LBB0_330
